# NA attention: QK K-fragment reads batched; q-fragment wait hoisted out of tile loop (no per-tile vmcnt stall on K/V prefetch)
# baseline (speedup 1.0000x reference)
; __device__ __forceinline__ int v_st(int k, int c) { const int kk = (k & ~0xC) | ((k & 4) << 1) | ((k & 8) >> 1); return ((kk >> 3) * 4 + (c >> 5)) * 512 + ((kk & 7) * 32 + (c & 31)) * 2; }
; __device__ __forceinline__ int v_rd_base(int lane) { return ((lane & 3) << 3) | (((lane >> 2) & 3) << 6) | (((lane >> 4) & 1) << 5) | (((lane >> 5) & 1) << 8); }
; __device__ __forceinline__ void na_unit(const bf16_t* __restrict__ QKV, bf16_t* __restrict__ O, const float* __restrict__ rpb, int tok0, int rows, int g4, int h, char* lds) {
;     ...
;   const int tid = tid_, wid = __builtin_amdgcn_readfirstlane(tid >> 6), lane = tid & 63, r32 = lane & 31, hi = lane >> 5;
;   const int qr = 4 * g4 + (wid >> 1), qh = wid & 1, c = 32 * qh + r32;
;   const int krlo = min(max(4 * g4 - 4, 0), rows - 8), krhi = min(max(4 * g4 - 1, 0), rows - 8) + 7, nt = krhi - krlo + 1;
;   const int r0w = min(max(qr - 4, 0), rows - 8), c0 = min(max(c - 8, 0), 48);
;   float* T = (float*)(lds + OFF_T); float* ws = (float*)(lds + OFF_WS) + wid * 64; float* li_l = ws; float* al_l = ws + 32;
;   if (tid < 465) { const int rr = tid / 31, cc = tid - rr * 31; T[rr * 128 + 48 + cc] = rpb[h * 465 + tid]; }
;   bf16x8 qf[4];
;   { const bf16_t* qp = QKV + (size_t)(tok0 + qr * 64 + c) * 3072 + h * 64 + hi * 8;
; #pragma unroll
;     for (int d0 = 0; d0 < 4; ++d0) qf[d0] = *reinterpret_cast<const bf16x8*>(qp + d0 * 16); }
;   const int skey = tid >> 3, sch = tid & 7;
;   const bf16_t* kg = QKV + (size_t)(tok0 + krlo * 64 + skey) * 3072 + 1024 + h * 64 + sch * 8;
;   const int kst = skey * 144 + sch * 16, vst = v_st(skey, sch * 8);
;   const int vb0 = (int)(uintptr_t)(lds + OFF_V) + v_rd_base(lane);
;   bf16x8 sk, sv;
;   sk = *(const bf16x8*)kg; sv = *(const bf16x8*)(kg + 1024);
;   asm volatile("s_waitcnt vmcnt(0)" ::: "memory");
;   *(bf16x8*)(lds + OFF_K + kst) = sk; *(bf16x8*)(lds + OFF_V + vst) = sv;
;   __syncthreads();
.LBB0_383:
	s_or_b64 exec, exec, s[2:3]
	s_lshr_b32 s3, s7, 4
	s_lshl_b32 s5, s7, 4
	s_cmpk_lt_i32 s7, 0x400
	s_cselect_b32 s9, 7, 31
	s_mov_b32 s2, 0x7fffe000
	s_cselect_b32 s12, 0xfffff800, s2
	s_cselect_b32 s2, 24, 0x78
	s_and_b32 s3, s3, s9
	s_lshl_b32 s13, s3, 2
	v_sub_u32_e64 v0, s13, 4 clamp
	s_and_b32 s5, s5, s12
	s_ashr_i32 s70, s4, 7
	v_readfirstlane_b32 s12, v0
	s_add_i32 s3, s70, s13
	s_lshr_b32 s9, s4, 1
	s_min_u32 s15, s12, s2
	s_waitcnt vmcnt(6)
	v_and_b32_e32 v109, 31, v5
	s_and_b32 s9, s9, 32
	s_lshl_b32 s14, s3, 6
	s_lshl_b32 s12, s15, 6
	v_or_b32_e32 v4, s9, v109
	s_add_i32 s14, s14, s5
	v_ashrrev_i32_e32 v7, 3, v5
	s_add_i32 s12, s12, s5
	v_or_b32_e32 v0, s14, v4
	v_mov_b64_e32 v[8:9], s[56:57]
	v_add_u32_e32 v6, s12, v7
	v_mad_i64_i32 v[2:3], s[16:17], v0, s63, v[8:9]
	s_lshl_b32 s76, s8, 7
	v_and_b32_e32 v0, 7, v5
	v_mad_i64_i32 v[8:9], s[16:17], v6, s63, v[8:9]
	v_bfe_u32 v108, v5, 5, 1
	v_lshl_add_u64 v[8:9], v[8:9], 0, s[76:77]
	v_lshlrev_b32_e32 v0, 4, v0
	s_waitcnt vmcnt(4)
	v_lshl_add_u64 v[10:11], v[2:3], 0, s[76:77]
	v_lshlrev_b32_e32 v2, 4, v108
	v_mov_b32_e32 v3, v1
	v_lshl_add_u64 v[8:9], v[8:9], 0, v[0:1]
	s_mov_b64 s[16:17], 0x800
	v_lshl_add_u64 v[12:13], v[8:9], 0, s[16:17]
	global_load_dwordx4 v[82:85], v[8:9], off offset:2048
	global_load_dwordx4 v[90:93], v[12:13], off offset:2048
	v_lshl_add_u64 v[8:9], v[10:11], 0, v[2:3]
	global_load_dwordx4 v[86:89], v[8:9], off
	global_load_dwordx4 v[94:97], v[8:9], off offset:32
	global_load_dwordx4 v[98:101], v[8:9], off offset:64
	global_load_dwordx4 v[102:105], v[8:9], off offset:96
	v_and_b32_e32 v8, 0xfffff0, v7
	v_lshlrev_b32_e32 v9, 1, v7
	v_and_b32_e32 v112, 63, v5
	v_bfe_u32 v3, v5, 2, 1
	v_mul_lo_u32 v5, v7, s74
	v_and_or_b32 v8, v9, 8, v8
	s_waitcnt vmcnt(8)
	v_add3_u32 v49, 0, v5, v0
	v_lshrrev_b32_e32 v5, 1, v8
	v_or_b32_e32 v3, v5, v3
	v_sub_u32_e64 v5, s13, 1 clamp
	v_lshrrev_b32_e32 v10, 1, v7
	v_readfirstlane_b32 s5, v5
	v_and_b32_e32 v7, 3, v7
	s_and_b32 s4, s4, 0x3fffffc0
	s_min_u32 s5, s5, s2
	v_and_or_b32 v7, v10, 4, v7
	s_lshl_b32 s4, s4, 2
	s_sub_i32 s12, s5, s15
	s_waitcnt vmcnt(0)
	v_lshlrev_b32_e32 v111, 2, v108
	v_and_b32_e32 v9, 48, v0
	v_lshlrev_b32_e32 v7, 6, v7
	s_add_i32 s4, s4, 0
	v_lshl_add_u32 v3, v3, 9, 0
	s_add_i32 s21, s12, 7
	s_mov_b32 s20, 0
	v_cmp_gt_u32_e64 s[38:39], 32, v112
	v_lshl_add_u32 v113, v109, 2, s4
	v_add3_u32 v114, v3, v7, v9
	s_cmp_lt_i32 s21, 0
	v_lshl_add_u32 v110, v111, 2, s4
	s_waitcnt vmcnt(5)
	ds_write_b128 v49, v[82:85] offset:32768
	s_waitcnt vmcnt(0)
	ds_write_b128 v114, v[90:93]
	s_waitcnt lgkmcnt(0)
	s_barrier
	s_cbranch_scc1 .LBB0_460
; __device__ __forceinline__ void na_unit(const bf16_t* __restrict__ QKV, bf16_t* __restrict__ O, const float* __restrict__ rpb, int tok0, int rows, int g4, int h, char* lds) {
;     ...
;   float m_reg = -1e30f, l_reg = 0.f; f32x16 o[2] = {};
;   const int tb = (48 - c + 15 + 4 * hi);
;   for (int t = 0; t < nt; ++t) {
;     const int buf = t & 1, kr = krlo + t;
;     if (t + 1 < nt) { sk = *(const bf16x8*)(kg + (size_t)(t + 1) * 64 * 3072); sv = *(const bf16x8*)(kg + (size_t)(t + 1) * 64 * 3072 + 1024); }
;     if (kr >= r0w && kr <= r0w + 7) {
;       const char* Ks = lds + OFF_K + buf * SHM_K;
;       f32x16 p0 = {}, p1 = {};
; #pragma unroll
;       for (int d0 = 0; d0 < 4; ++d0) { const int cb = (d0 * 16 + hi * 8) * 2;
;         const bf16x8 b0 = *reinterpret_cast<const bf16x8*>(Ks + r32 * 144 + cb), b1 = *reinterpret_cast<const bf16x8*>(Ks + (32 + r32) * 144 + cb);
;         p0 = __builtin_amdgcn_mfma_f32_32x32x16_bf16(b0, qf[d0], p0, 0, 0, 0); p1 = __builtin_amdgcn_mfma_f32_32x32x16_bf16(b1, qf[d0], p1, 0, 0, 0); }
;       const float* Tr = T + (kr - qr + 7) * 128 + tb;
; #pragma unroll
;       for (int r = 0; r < 16; ++r) { const int ko = (r & 3) + 8 * (r >> 2), kc = ko + 4 * hi;
;         const bool v0 = (kc >= c0) && (kc <= c0 + 15), v1 = (kc + 32 >= c0) && (kc + 32 <= c0 + 15);
	v_xor_b32_e32 v3, 63, v4
	v_sub_u32_e64 v4, v4, 8 clamp
	v_min_u32_e32 v4, 48, v4
	v_add_u32_e32 v11, 15, v4
	v_or_b32_e32 v12, 32, v111
	v_cmp_ge_u32_e32 vcc, v12, v4
	v_cmp_le_u32_e64 s[42:43], v12, v11
	v_or_b32_e32 v12, 1, v111
	s_and_b64 s[26:27], vcc, s[42:43]
	v_cmp_ge_u32_e64 s[42:43], v12, v4
	v_or_b32_e32 v12, 33, v111
	v_cmp_ge_u32_e32 vcc, v12, v4
	v_cmp_le_u32_e64 s[44:45], v12, v11
	v_or_b32_e32 v12, 2, v111
	s_and_b64 s[34:35], vcc, s[44:45]
	v_cmp_ge_u32_e64 s[44:45], v12, v4
	v_or_b32_e32 v12, 34, v111
	v_cmp_ge_u32_e32 vcc, v12, v4
	v_cmp_le_u32_e64 s[46:47], v12, v11
	v_or_b32_e32 v12, 3, v111
	s_and_b64 s[78:79], vcc, s[46:47]
	v_cmp_ge_u32_e64 s[46:47], v12, v4
	v_or_b32_e32 v12, 35, v111
	v_cmp_ge_u32_e32 vcc, v12, v4
	v_cmp_le_u32_e64 s[48:49], v12, v11
	v_or_b32_e32 v12, 8, v111
	s_and_b64 s[80:81], vcc, s[48:49]
	v_cmp_ge_u32_e64 s[48:49], v12, v4
	v_or_b32_e32 v12, 40, v111
	v_cmp_ge_u32_e32 vcc, v12, v4
	v_cmp_le_u32_e64 s[50:51], v12, v11
	v_or_b32_e32 v12, 9, v111
	s_and_b64 s[82:83], vcc, s[50:51]
	v_cmp_ge_u32_e64 s[50:51], v12, v4
	v_or_b32_e32 v12, 41, v111
	v_cmp_ge_u32_e32 vcc, v12, v4
	v_cmp_le_u32_e64 s[52:53], v12, v11
	v_or_b32_e32 v12, 10, v111
	s_and_b64 s[84:85], vcc, s[52:53]
	v_cmp_ge_u32_e64 s[52:53], v12, v4
	v_or_b32_e32 v12, 42, v111
	v_cmp_ge_u32_e32 vcc, v12, v4
	v_cmp_le_u32_e64 s[54:55], v12, v11
	v_or_b32_e32 v12, 11, v111
	s_and_b64 s[86:87], vcc, s[54:55]
	v_cmp_ge_u32_e64 s[54:55], v12, v4
	v_or_b32_e32 v12, 43, v111
	v_cmp_ge_u32_e32 vcc, v12, v4
	v_cmp_le_u32_e64 s[56:57], v12, v11
	v_or_b32_e32 v12, 16, v111
	s_and_b64 s[88:89], vcc, s[56:57]
	v_cmp_ge_u32_e32 vcc, v12, v4
	v_cmp_le_u32_e64 s[56:57], v12, v11
	v_or_b32_e32 v12, 48, v111
	s_and_b64 s[90:91], vcc, s[56:57]
	v_cmp_le_u32_e64 s[56:57], v12, v11
	v_or_b32_e32 v12, 17, v111
	v_cmp_ge_u32_e32 vcc, v12, v4
	v_cmp_le_u32_e64 s[58:59], v12, v11
	v_or_b32_e32 v12, 49, v111
	s_and_b64 s[16:17], vcc, s[58:59]
	v_cmp_le_u32_e64 s[58:59], v12, v11
	v_or_b32_e32 v12, 18, v111
	v_cmp_ge_u32_e32 vcc, v12, v4
	v_cmp_le_u32_e64 s[60:61], v12, v11
	v_or_b32_e32 v12, 50, v111
	v_mad_i64_i32 v[6:7], s[4:5], v6, s63, 0
	s_and_b64 s[96:97], vcc, s[60:61]
	v_cmp_le_u32_e64 s[60:61], v12, v11
	v_or_b32_e32 v12, 19, v111
	s_and_b32 s4, s6, 15
	v_cmp_ge_u32_e32 vcc, v12, v4
	v_cmp_le_u32_e64 s[62:63], v12, v11
	v_or_b32_e32 v12, 51, v111
	s_lshl_b32 s76, s4, 7
	s_and_b64 s[4:5], vcc, s[62:63]
	v_cmp_le_u32_e64 s[62:63], v12, v11
	v_or_b32_e32 v12, 24, v111
	v_cmp_ge_u32_e32 vcc, v12, v4
	v_cmp_le_u32_e64 s[64:65], v12, v11
	v_or_b32_e32 v12, 56, v111
	s_max_i32 s3, s3, 4
	s_and_b64 s[18:19], vcc, s[64:65]
	v_cmp_le_u32_e64 s[64:65], v12, v11
	v_or_b32_e32 v12, 25, v111
	s_add_i32 s3, s3, -4
	v_cmp_ge_u32_e32 vcc, v12, v4
	v_cmp_le_u32_e64 s[66:67], v12, v11
	v_or_b32_e32 v12, 57, v111
	s_min_u32 s23, s3, s2
	s_and_b64 s[2:3], vcc, s[66:67]
	v_cmp_le_u32_e64 s[66:67], v12, v11
	v_or_b32_e32 v12, 26, v111
	v_cmp_ge_u32_e32 vcc, v12, v4
	v_cmp_le_u32_e64 s[68:69], v12, v11
	v_or_b32_e32 v13, 27, v111
	s_and_b64 s[28:29], vcc, s[68:69]
	v_cmp_ge_u32_e32 vcc, v13, v4
	v_cmp_le_u32_e64 s[68:69], v13, v11
	s_mov_b64 s[98:99], s[92:93]
	s_mov_b32 s92, s33
	s_mov_b32 s33, s95
	v_lshlrev_b32_e32 v5, 3, v112
	s_add_i32 s95, s23, 7
	s_add_i32 s12, s12, 8
	s_and_b64 s[72:73], vcc, s[68:69]
	v_lshlrev_b32_e32 v8, 1, v112
	v_and_b32_e32 v5, 0x118, v5
	v_lshlrev_b32_e32 v9, 4, v112
	s_cmp_lg_u32 0, -1
	v_and_b32_e32 v9, 0xc0, v9
	v_cmp_ge_u32_e64 s[40:41], v111, v4
	v_and_or_b32 v4, v8, 32, v5
	s_cselect_b32 s24, 0, 0
	v_add3_u32 v115, v9, s24, v4
	s_sub_i32 s24, s15, s70
	s_sub_i32 s13, s24, s13
	v_mul_u32_u24_e32 v10, 0x90, v109
	v_lshl_or_b32 v5, s13, 9, v2
	v_lshlrev_b32_e32 v3, 2, v3
	s_add_i32 s13, 0, 0xd600
	v_add3_u32 v116, v5, v3, s13
	v_add3_u32 v117, 0, v10, v2
	v_lshl_add_u64 v[2:3], v[6:7], 0, s[76:77]
	v_readlane_b32 s24, v253, 38
	v_or_b32_e32 v12, 58, v111
	v_or_b32_e32 v4, 59, v111
	v_lshl_add_u64 v[2:3], v[2:3], 0, v[0:1]
	v_readlane_b32 s25, v253, 39
	v_mov_b32_e32 v14, v1
	v_mov_b32_e32 v15, v1
	v_cmp_le_u32_e64 s[68:69], v12, v11
	v_cmp_le_u32_e64 s[70:71], v4, v11
	v_lshl_add_u64 v[106:107], s[24:25], 0, v[2:3]
	v_mov_b32_e32 v0, v1
	v_mov_b32_e32 v2, v1
	v_mov_b32_e32 v3, v1
	v_mov_b32_e32 v4, v1
	v_mov_b32_e32 v5, v1
	v_mov_b32_e32 v6, v1
	v_mov_b32_e32 v7, v1
	v_mov_b32_e32 v8, v1
	v_mov_b32_e32 v9, v1
	v_mov_b32_e32 v10, v1
	v_mov_b32_e32 v11, v1
	v_mov_b32_e32 v12, v1
	v_mov_b32_e32 v13, v1
	v_mov_b64_e32 v[30:31], v[14:15]
	v_mov_b64_e32 v[46:47], v[14:15]
	v_mov_b32_e32 v48, 0
	v_mov_b32_e32 v118, 0xf149f2ca
	v_mov_b64_e32 v[28:29], v[12:13]
	v_mov_b64_e32 v[26:27], v[10:11]
	v_mov_b64_e32 v[24:25], v[8:9]
	v_mov_b64_e32 v[22:23], v[6:7]
	v_mov_b64_e32 v[20:21], v[4:5]
	v_mov_b64_e32 v[18:19], v[2:3]
	v_mov_b64_e32 v[16:17], v[0:1]
	v_mov_b64_e32 v[44:45], v[12:13]
	v_mov_b64_e32 v[42:43], v[10:11]
	v_mov_b64_e32 v[40:41], v[8:9]
	v_mov_b64_e32 v[38:39], v[6:7]
	v_mov_b64_e32 v[36:37], v[4:5]
	v_mov_b64_e32 v[34:35], v[2:3]
	v_mov_b64_e32 v[32:33], v[0:1]
	s_branch .LBB0_386

; __device__ __forceinline__ void na_unit(const bf16_t* __restrict__ QKV, bf16_t* __restrict__ O, const float* __restrict__ rpb, int tok0, int rows, int g4, int h, char* lds) {
;     ...
;       f32x16 p0 = {}, p1 = {};
; #pragma unroll
;       for (int d0 = 0; d0 < 4; ++d0) { const int cb = (d0 * 16 + hi * 8) * 2;
;         const bf16x8 b0 = *reinterpret_cast<const bf16x8*>(Ks + r32 * 144 + cb), b1 = *reinterpret_cast<const bf16x8*>(Ks + (32 + r32) * 144 + cb);
;         p0 = __builtin_amdgcn_mfma_f32_32x32x16_bf16(b0, qf[d0], p0, 0, 0, 0); p1 = __builtin_amdgcn_mfma_f32_32x32x16_bf16(b1, qf[d0], p1, 0, 0, 0); }
;       const float* Tr = T + (kr - qr + 7) * 128 + tb;
; #pragma unroll
;       for (int r = 0; r < 16; ++r) { const int ko = (r & 3) + 8 * (r >> 2), kc = ko + 4 * hi;
;         const bool v0 = (kc >= c0) && (kc <= c0 + 15), v1 = (kc + 32 >= c0) && (kc + 32 <= c0 + 15);
;         p0[r] = v0 ? fmaf(p0[r], 0.125f, Tr[ko]) : -1e30f; p1[r] = v1 ? fmaf(p1[r], 0.125f, Tr[ko + 32]) : -1e30f; }
.LBB0_388:
	s_and_b32 s13, s20, 1
	s_add_i32 s24, s15, s20
	s_cmp_lt_u32 s24, s23
	s_cselect_b64 vcc, -1, 0
	s_cmp_gt_u32 s24, s95
	s_cselect_b64 s[24:25], -1, 0
	s_or_b64 s[24:25], vcc, s[24:25]
	s_and_b64 vcc, exec, s[24:25]
	s_cbranch_vccnz .LBB0_458
	s_mul_i32 s24, s13, 0x2400
	v_add_u32_e32 v0, s24, v117
	ds_read_b128 v[154:157], v0 offset:32768
	ds_read_b128 v[158:161], v0 offset:37376
	ds_read_b128 v[162:165], v0 offset:32800
	ds_read_b128 v[166:169], v0 offset:37408
	ds_read_b128 v[170:173], v0 offset:32832
	ds_read_b128 v[174:177], v0 offset:37440
	ds_read_b128 v[178:181], v0 offset:32864
	ds_read_b128 v[182:185], v0 offset:37472
	s_waitcnt lgkmcnt(6)
	v_mfma_f32_32x32x16_bf16 v[66:81], v[154:157], v[86:89], 0
	v_mfma_f32_32x32x16_bf16 v[50:65], v[158:161], v[86:89], 0
	s_waitcnt lgkmcnt(4)
	v_mfma_f32_32x32x16_bf16 v[66:81], v[162:165], v[94:97], v[66:81]
	v_mfma_f32_32x32x16_bf16 v[50:65], v[166:169], v[94:97], v[50:65]
	s_waitcnt lgkmcnt(2)
	v_mfma_f32_32x32x16_bf16 v[66:81], v[170:173], v[98:101], v[66:81]
	v_mfma_f32_32x32x16_bf16 v[50:65], v[174:177], v[98:101], v[50:65]
	s_waitcnt lgkmcnt(0)
	v_mfma_f32_32x32x16_bf16 v[66:81], v[178:181], v[102:105], v[66:81]
	v_mfma_f32_32x32x16_bf16 v[50:65], v[182:185], v[102:105], v[50:65]
	ds_read_b32 v120, v116 offset:0
	ds_read_b32 v121, v116 offset:128
	ds_read_b32 v122, v116 offset:4
	ds_read_b32 v123, v116 offset:132
	ds_read_b32 v124, v116 offset:8
	ds_read_b32 v125, v116 offset:136
	ds_read_b32 v126, v116 offset:12
	ds_read_b32 v127, v116 offset:140
	ds_read_b32 v128, v116 offset:32
	ds_read_b32 v129, v116 offset:160
	ds_read_b32 v130, v116 offset:36
	ds_read_b32 v131, v116 offset:164
	v_mov_b32_e32 v152, 0xf149f2ca
	s_waitcnt lgkmcnt(0)
	ds_read_b32 v132, v116 offset:40
	ds_read_b32 v133, v116 offset:168
	ds_read_b32 v134, v116 offset:44
	ds_read_b32 v135, v116 offset:172
	ds_read_b32 v136, v116 offset:64
	ds_read_b32 v137, v116 offset:192
	ds_read_b32 v138, v116 offset:68
	ds_read_b32 v139, v116 offset:196
	ds_read_b32 v140, v116 offset:72
	ds_read_b32 v141, v116 offset:200
	ds_read_b32 v142, v116 offset:76
	ds_read_b32 v143, v116 offset:204
	v_fmac_f32_e32 v120, 0x3e000000, v66
	v_fmac_f32_e32 v121, 0x3e000000, v50
	v_fmac_f32_e32 v122, 0x3e000000, v67
	v_fmac_f32_e32 v123, 0x3e000000, v51
	v_fmac_f32_e32 v124, 0x3e000000, v68
	v_fmac_f32_e32 v125, 0x3e000000, v52
	v_fmac_f32_e32 v126, 0x3e000000, v69
	v_fmac_f32_e32 v127, 0x3e000000, v53
	v_fmac_f32_e32 v128, 0x3e000000, v70
	v_fmac_f32_e32 v129, 0x3e000000, v54
	v_fmac_f32_e32 v130, 0x3e000000, v71
	v_fmac_f32_e32 v131, 0x3e000000, v55
	s_waitcnt lgkmcnt(0)
	ds_read_b32 v144, v116 offset:96
	ds_read_b32 v145, v116 offset:224
	ds_read_b32 v146, v116 offset:100
	ds_read_b32 v147, v116 offset:228
	ds_read_b32 v148, v116 offset:104
	ds_read_b32 v149, v116 offset:232
	ds_read_b32 v150, v116 offset:108
	ds_read_b32 v151, v116 offset:236
	v_fmac_f32_e32 v132, 0x3e000000, v72
	v_fmac_f32_e32 v133, 0x3e000000, v56
	v_fmac_f32_e32 v134, 0x3e000000, v73
	v_fmac_f32_e32 v135, 0x3e000000, v57
	v_fmac_f32_e32 v136, 0x3e000000, v74
	v_fmac_f32_e32 v137, 0x3e000000, v58
	v_fmac_f32_e32 v138, 0x3e000000, v75
	v_fmac_f32_e32 v139, 0x3e000000, v59
	v_fmac_f32_e32 v140, 0x3e000000, v76
	v_fmac_f32_e32 v141, 0x3e000000, v60
	v_fmac_f32_e32 v142, 0x3e000000, v77
	v_fmac_f32_e32 v143, 0x3e000000, v61
	s_waitcnt lgkmcnt(0)
	v_fmac_f32_e32 v144, 0x3e000000, v78
	v_fmac_f32_e32 v145, 0x3e000000, v62
	v_fmac_f32_e32 v146, 0x3e000000, v79
	v_fmac_f32_e32 v147, 0x3e000000, v63
	v_fmac_f32_e32 v148, 0x3e000000, v80
	v_fmac_f32_e32 v149, 0x3e000000, v64
	v_fmac_f32_e32 v150, 0x3e000000, v81
	v_fmac_f32_e32 v151, 0x3e000000, v65
	v_cndmask_b32_e64 v2, v152, v120, s[40:41]
	v_cndmask_b32_e64 v0, v152, v121, s[26:27]
	v_cndmask_b32_e64 v4, v152, v122, s[42:43]
	v_cndmask_b32_e64 v3, v152, v123, s[34:35]
	v_cndmask_b32_e64 v6, v152, v124, s[44:45]
	v_cndmask_b32_e64 v5, v152, v125, s[78:79]
	v_cndmask_b32_e64 v8, v152, v126, s[46:47]
	v_cndmask_b32_e64 v7, v152, v127, s[80:81]
	v_cndmask_b32_e64 v10, v152, v128, s[48:49]
	v_cndmask_b32_e64 v9, v152, v129, s[82:83]
	v_cndmask_b32_e64 v12, v152, v130, s[50:51]
	v_cndmask_b32_e64 v11, v152, v131, s[84:85]
	v_cndmask_b32_e64 v14, v152, v132, s[52:53]
	v_cndmask_b32_e64 v13, v152, v133, s[86:87]
	v_cndmask_b32_e64 v50, v152, v134, s[54:55]
	v_cndmask_b32_e64 v15, v152, v135, s[88:89]
	v_cndmask_b32_e64 v52, v152, v136, s[90:91]
	v_cndmask_b32_e64 v51, v152, v137, s[56:57]
	v_cndmask_b32_e64 v55, v152, v138, s[16:17]
	v_cndmask_b32_e64 v53, v152, v139, s[58:59]
	v_cndmask_b32_e64 v57, v152, v140, s[96:97]
	v_cndmask_b32_e64 v56, v152, v141, s[60:61]
	v_cndmask_b32_e64 v59, v152, v142, s[4:5]
	v_cndmask_b32_e64 v58, v152, v143, s[62:63]
	v_cndmask_b32_e64 v61, v152, v144, s[18:19]
	v_cndmask_b32_e64 v60, v152, v145, s[64:65]
	v_cndmask_b32_e64 v66, v152, v146, s[2:3]
	v_cndmask_b32_e64 v62, v152, v147, s[66:67]
	v_cndmask_b32_e64 v67, v152, v148, s[28:29]
	v_cndmask_b32_e64 v63, v152, v149, s[68:69]
	v_cndmask_b32_e64 v68, v152, v150, s[72:73]
	v_cndmask_b32_e64 v64, v152, v151, s[70:71]
	v_max_f32_e32 v54, v4, v4
	v_max_f32_e32 v65, v2, v2
	v_max_f32_e32 v54, v65, v54
	v_max3_f32 v54, v54, v6, v8
	v_max3_f32 v54, v54, v10, v12
	v_max3_f32 v54, v54, v14, v50
	v_max3_f32 v54, v54, v52, v55
	v_max3_f32 v54, v54, v57, v59
	v_max3_f32 v54, v54, v61, v66
	v_max3_f32 v54, v54, v67, v68
	v_max3_f32 v54, v54, v0, v3
	v_max3_f32 v54, v54, v5, v7
	v_max3_f32 v54, v54, v9, v11
	v_max3_f32 v54, v54, v13, v15
; __device__ __forceinline__ int crow(int r, int hi) { return (r & 3) + 8 * (r >> 2) + 4 * hi; }
; template <int DQK> __device__ __forceinline__ void partialSM(f32x16& p0, f32x16& p1, float& m_reg, float& mn, float& alpha) {
;   constexpr float SCALE = (DQK == 192) ? 0.07216878364870322f : (DQK == 64 ? 1.0f : 0.08838834764831845f);
;   constexpr float C = SCALE * 1.4426950408889634f;
;   float pmax = p0[0];
; #pragma unroll
;   for (int r = 1; r < 16; ++r) pmax = fmaxf(pmax, p0[r]);
; #pragma unroll
;   for (int r = 0; r < 16; ++r) pmax = fmaxf(pmax, p1[r]);
;   { auto rr = __builtin_amdgcn_permlane32_swap(__float_as_uint(pmax), __float_as_uint(pmax), false, false);
;     pmax = fmaxf(__uint_as_float(rr[0]), __uint_as_float(rr[1])); }
;   if (__builtin_expect(__all(pmax - m_reg <= THR / SCALE), 1)) { mn = m_reg; alpha = 1.f; }
;   else { mn = fmaxf(m_reg, pmax); alpha = __builtin_amdgcn_exp2f((m_reg - mn) * C); m_reg = mn; }
;   float mnC = -mn * C;
; #pragma unroll
;   for (int r = 0; r < 16; ++r) p0[r] = fmaf(p0[r], C, mnC);
; #pragma unroll
;   for (int r = 0; r < 16; ++r) p1[r] = fmaf(p1[r], C, mnC);
; #pragma unroll
;   for (int r = 0; r < 16; ++r) p0[r] = __builtin_amdgcn_exp2f(p0[r]);
; }
; __device__ __forceinline__ void finishSM(f32x16& p0, f32x16& p1, float alpha, float& l_reg, bf16x8& pa0, bf16x8& pa1, bf16x8& pa2, bf16x8& pa3) {
; #pragma unroll
;   for (int r = 0; r < 16; ++r) p1[r] = __builtin_amdgcn_exp2f(p1[r]);
;   float ps = 0;
; #pragma unroll
;   for (int r = 0; r < 16; ++r) ps += p0[r];
; #pragma unroll
;   for (int r = 0; r < 16; ++r) ps += p1[r];
;   { auto rr = __builtin_amdgcn_permlane32_swap(__float_as_uint(ps), __float_as_uint(ps), false, false);
;     ps = __uint_as_float(rr[0]) + __uint_as_float(rr[1]); }
;   l_reg = l_reg * alpha + ps;
;     ...
;   PK4(p0, 0, pa0); PK4(p0, 8, pa1); PK4(p1, 0, pa2); PK4(p1, 8, pa3);
;     ...
; }
; __device__ __forceinline__ void na_unit(const bf16_t* __restrict__ QKV, bf16_t* __restrict__ O, const float* __restrict__ rpb, int tok0, int rows, int g4, int h, char* lds) {
;     ...
;       if (__any(al < 1.f)) { if (hi == 0) al_l[r32] = al; asm volatile("s_waitcnt lgkmcnt(0)" ::: "memory");
; #pragma unroll
;         for (int d = 0; d < 2; ++d)
; #pragma unroll
;           for (int r = 0; r < 16; ++r) o[d][r] *= al_l[crow(r, hi)]; }
	v_max3_f32 v54, v54, v51, v53
	v_max3_f32 v54, v54, v56, v58
	v_max3_f32 v54, v54, v60, v62
	v_max3_f32 v54, v54, v63, v64
	v_mov_b32_e32 v65, v54
	s_nop 1
	v_permlane32_swap_b32_e32 v54, v65
	v_max_f32_e32 v65, v65, v65
	v_max_f32_e32 v54, v54, v54
	v_max_f32_e32 v54, v54, v65
	v_sub_f32_e32 v65, v54, v118
	s_mov_b32 s24, 0x41000000
	v_cmp_ge_f32_e32 vcc, s24, v65
	v_max_f32_e32 v69, v118, v118
	s_cmp_eq_u64 vcc, exec
	v_max_f32_e32 v69, v69, v54
	s_cselect_b64 vcc, -1, 0
	v_sub_f32_e32 v54, v118, v69
	v_cndmask_b32_e32 v118, v69, v118, vcc
	v_mul_f32_e32 v65, 0xbfb8aa3b, v118
	v_fmamk_f32 v2, v2, 0x3fb8aa3b, v65
	v_fmamk_f32 v4, v4, 0x3fb8aa3b, v65
	v_exp_f32_e32 v2, v2
	v_fmamk_f32 v6, v6, 0x3fb8aa3b, v65
	v_exp_f32_e32 v4, v4
	v_fmamk_f32 v8, v8, 0x3fb8aa3b, v65
	v_exp_f32_e32 v6, v6
	v_fmamk_f32 v10, v10, 0x3fb8aa3b, v65
	v_fmamk_f32 v0, v0, 0x3fb8aa3b, v65
	v_exp_f32_e32 v8, v8
	v_fmamk_f32 v12, v12, 0x3fb8aa3b, v65
	v_exp_f32_e32 v10, v10
	v_exp_f32_e32 v69, v0
	v_add_f32_e32 v0, 0, v2
	v_fmamk_f32 v14, v14, 0x3fb8aa3b, v65
	v_exp_f32_e32 v12, v12
	v_add_f32_e32 v0, v4, v0
	v_fmamk_f32 v50, v50, 0x3fb8aa3b, v65
	v_fmamk_f32 v52, v52, 0x3fb8aa3b, v65
	v_fmamk_f32 v55, v55, 0x3fb8aa3b, v65
	v_fmamk_f32 v57, v57, 0x3fb8aa3b, v65
	v_fmamk_f32 v59, v59, 0x3fb8aa3b, v65
	v_fmamk_f32 v61, v61, 0x3fb8aa3b, v65
	v_fmamk_f32 v66, v66, 0x3fb8aa3b, v65
	v_fmamk_f32 v67, v67, 0x3fb8aa3b, v65
	v_fmamk_f32 v68, v68, 0x3fb8aa3b, v65
	v_fmamk_f32 v3, v3, 0x3fb8aa3b, v65
	v_fmamk_f32 v5, v5, 0x3fb8aa3b, v65
	v_fmamk_f32 v7, v7, 0x3fb8aa3b, v65
	v_fmamk_f32 v9, v9, 0x3fb8aa3b, v65
	v_fmamk_f32 v11, v11, 0x3fb8aa3b, v65
	v_fmamk_f32 v13, v13, 0x3fb8aa3b, v65
	v_fmamk_f32 v15, v15, 0x3fb8aa3b, v65
	v_fmamk_f32 v51, v51, 0x3fb8aa3b, v65
	v_fmamk_f32 v53, v53, 0x3fb8aa3b, v65
	v_fmamk_f32 v56, v56, 0x3fb8aa3b, v65
	v_fmamk_f32 v58, v58, 0x3fb8aa3b, v65
	v_fmamk_f32 v60, v60, 0x3fb8aa3b, v65
	v_fmamk_f32 v62, v62, 0x3fb8aa3b, v65
	v_fmamk_f32 v63, v63, 0x3fb8aa3b, v65
	v_fmac_f32_e32 v65, 0x3fb8aa3b, v64
	v_exp_f32_e32 v64, v14
	v_add_f32_e32 v0, v6, v0
	v_exp_f32_e32 v50, v50
	v_add_f32_e32 v0, v8, v0
	v_exp_f32_e32 v52, v52
	v_add_f32_e32 v0, v10, v0
	v_exp_f32_e32 v55, v55
	v_add_f32_e32 v0, v12, v0
	v_exp_f32_e32 v57, v57
	v_add_f32_e32 v0, v64, v0
	v_exp_f32_e32 v59, v59
	v_add_f32_e32 v0, v50, v0
	v_exp_f32_e32 v61, v61
	v_add_f32_e32 v0, v52, v0
	v_exp_f32_e32 v66, v66
	v_add_f32_e32 v0, v55, v0
	v_exp_f32_e32 v67, v67
	v_add_f32_e32 v0, v57, v0
	v_exp_f32_e32 v68, v68
	v_add_f32_e32 v0, v59, v0
	v_add_f32_e32 v0, v61, v0
	v_exp_f32_e32 v70, v3
	v_add_f32_e32 v0, v66, v0
	v_exp_f32_e32 v71, v5
	v_add_f32_e32 v0, v67, v0
	v_exp_f32_e32 v72, v7
	v_add_f32_e32 v0, v68, v0
	v_exp_f32_e32 v73, v9
	v_add_f32_e32 v0, v69, v0
	v_exp_f32_e32 v74, v11
	v_add_f32_e32 v0, v70, v0
	v_exp_f32_e32 v13, v13
	v_add_f32_e32 v0, v71, v0
	v_exp_f32_e32 v15, v15
	v_add_f32_e32 v0, v72, v0
	v_exp_f32_e32 v51, v51
	v_add_f32_e32 v0, v73, v0
	v_exp_f32_e32 v53, v53
	v_add_f32_e32 v0, v74, v0
	v_exp_f32_e32 v56, v56
	v_add_f32_e32 v0, v13, v0
	v_exp_f32_e32 v58, v58
	v_add_f32_e32 v0, v15, v0
	v_exp_f32_e32 v60, v60
	v_add_f32_e32 v0, v51, v0
	v_exp_f32_e32 v62, v62
	v_add_f32_e32 v0, v53, v0
	v_exp_f32_e32 v63, v63
	v_add_f32_e32 v0, v56, v0
	v_mul_f32_e32 v54, 0x3fb8aa3b, v54
	v_exp_f32_e32 v65, v65
	v_add_f32_e32 v0, v58, v0
	v_exp_f32_e32 v54, v54
	v_add_f32_e32 v0, v60, v0
	v_add_f32_e32 v0, v62, v0
	v_add_f32_e32 v0, v63, v0
	v_add_f32_e32 v0, v65, v0
	v_cndmask_b32_e64 v54, v54, 1.0, vcc
	v_mov_b32_e32 v14, v0
	v_cvt_pk_bf16_f32 v2, v2, v4
	v_cvt_pk_bf16_f32 v3, v6, v8
	v_cvt_pk_bf16_f32 v4, v10, v12
	v_cvt_pk_bf16_f32 v5, v64, v50
	v_cvt_pk_bf16_f32 v6, v52, v55
	v_cvt_pk_bf16_f32 v7, v57, v59
	v_cvt_pk_bf16_f32 v8, v61, v66
	v_cvt_pk_bf16_f32 v9, v67, v68
	v_cvt_pk_bf16_f32 v10, v69, v70
	v_cvt_pk_bf16_f32 v11, v71, v72
	v_cvt_pk_bf16_f32 v12, v73, v74
	v_cvt_pk_bf16_f32 v13, v13, v15
	v_cvt_pk_bf16_f32 v50, v51, v53
	v_cvt_pk_bf16_f32 v51, v56, v58
	v_cvt_pk_bf16_f32 v52, v60, v62
	v_cvt_pk_bf16_f32 v53, v63, v65
	v_permlane32_swap_b32_e32 v0, v14
	v_permlane32_swap_b32_e32 v2, v4
	v_permlane32_swap_b32_e32 v3, v5
	v_permlane32_swap_b32_e32 v6, v8
	v_permlane32_swap_b32_e32 v7, v9
	v_permlane32_swap_b32_e32 v10, v12
	v_permlane32_swap_b32_e32 v11, v13
	v_permlane32_swap_b32_e32 v50, v52
	v_permlane32_swap_b32_e32 v51, v53
	v_cmp_gt_f32_e32 vcc, 1.0, v54
	s_cbranch_vccz .LBB0_457
	s_and_saveexec_b64 vcc, s[38:39]
	ds_write_b32 v113, v54 offset:59008
	s_or_b64 exec, exec, vcc
	s_waitcnt lgkmcnt(0)
	ds_read_b128 v[56:59], v110 offset:59104
	ds_read_b128 v[60:63], v110 offset:59072
	ds_read_b128 v[64:67], v110 offset:59040
	ds_read_b128 v[68:71], v110 offset:59008
	s_waitcnt lgkmcnt(3)
	v_pk_mul_f32 v[46:47], v[46:47], v[58:59]
	s_waitcnt lgkmcnt(2)
	v_pk_mul_f32 v[42:43], v[42:43], v[62:63]
	s_waitcnt lgkmcnt(1)
	v_pk_mul_f32 v[38:39], v[38:39], v[66:67]
	s_waitcnt lgkmcnt(0)
	v_pk_mul_f32 v[34:35], v[34:35], v[70:71]
	v_pk_mul_f32 v[44:45], v[44:45], v[56:57]
	v_pk_mul_f32 v[40:41], v[40:41], v[60:61]
	v_pk_mul_f32 v[36:37], v[36:37], v[64:65]
	v_pk_mul_f32 v[32:33], v[32:33], v[68:69]
	v_pk_mul_f32 v[30:31], v[30:31], v[58:59]
	v_pk_mul_f32 v[26:27], v[26:27], v[62:63]
	v_pk_mul_f32 v[22:23], v[22:23], v[66:67]
	v_pk_mul_f32 v[18:19], v[18:19], v[70:71]
	v_pk_mul_f32 v[28:29], v[28:29], v[56:57]
	v_pk_mul_f32 v[24:25], v[24:25], v[60:61]
	v_pk_mul_f32 v[20:21], v[20:21], v[64:65]
	v_pk_mul_f32 v[16:17], v[16:17], v[68:69]
